# placement test: hand-written UP epilogue shifted by 4 bytes (compensated behind it) on top of the combined variant
# speedup vs baseline: 1.0020x; 1.0020x over previous
;     __device__ __forceinline__ void operator()(const f32x4 (&acc)[2][2][4][2], const Unit& u, int wr, int wc, int fr, int fq) const {
;         int seqrow, tstart, T, vlo, vhi;
;         if (u.pm < 132) { const int b = u.pm / 33, i = u.pm - b * 33; seqrow = b * 8192; tstart = 254 * i - 1; T = 8192; vlo = 1; vhi = 255; }
;         else { seqrow = 32768 + (u.pm - 132) * 256; tstart = 0; T = 256; vlo = 0; vhi = 256; }
;         const bool edge = (tstart <= 0) || (tstart + 256 >= T);
;         const int ch0 = 128 * u.pn + 32 * wc + 8 * fq;
;         f32x4 w0[2], w1[2], w2[2], bb[2];
; #pragma unroll
;         for (int bj = 0; bj < 2; ++bj) { const int col = bj * 2816 + ch0;
;             w0[bj] = *(const f32x4*)(cw + col); w1[bj] = *(const f32x4*)(cw + 5632 + col); w2[bj] = *(const f32x4*)(cw + 11264 + col); bb[bj] = *(const f32x4*)(cb + col); }
; #pragma unroll
;         for (int ai = 0; ai < 2; ++ai) { const int blk = ai * 2 + wr;
;             if (fr == 0) {
; #pragma unroll
;                 for (int bj = 0; bj < 2; ++bj)
; #pragma unroll
;                     for (int n = 0; n < 2; ++n) *(PG8_LAS f32x4*)(xb + ((((blk * 2 + 0) * 4 + wc) * 4 + fq) * 16 + (bj * 2 + n) * 4)) = acc[ai][bj][0][n]; }
;             if (fr == 15) {
; #pragma unroll
;                 for (int bj = 0; bj < 2; ++bj)
; #pragma unroll
;                     for (int n = 0; n < 2; ++n) *(PG8_LAS f32x4*)(xb + ((((blk * 2 + 1) * 4 + wc) * 4 + fq) * 16 + (bj * 2 + n) * 4)) = acc[ai][bj][3][n]; } }
;         asm volatile("s_waitcnt lgkmcnt(0)" ::: "memory"); __builtin_amdgcn_s_barrier(); asm volatile("" ::: "memory");
;         const f32x4 zero4 = {0.f, 0.f, 0.f, 0.f};
; #pragma unroll
;         for (int n = 0; n < 2; ++n) {
;             if (n == 1) {
; #pragma unroll
;                 for (int bj = 0; bj < 2; ++bj) { const int col = bj * 2816 + ch0 + 4;
;                     w0[bj] = *(const f32x4*)(cw + col); w1[bj] = *(const f32x4*)(cw + 5632 + col); w2[bj] = *(const f32x4*)(cw + 11264 + col); bb[bj] = *(const f32x4*)(cb + col); } }
; #pragma unroll
;             for (int ai = 0; ai < 2; ++ai) { const int blk = ai * 2 + wr;
; #pragma unroll
;                 for (int m = 0; m < 4; ++m) { const int r = 128 * ai + 64 * wr + 16 * m + fr, t = tstart + r;
;                     const bool upok = t >= 1, dnok = (t + 1) < T, store_ok = (r >= vlo) && (r < vhi) && (t < T);
.LBB0_705:
	s_nop 0
	v_lshl_or_b32 v248, s2, 7, v229
	v_lshlrev_b32_e32 v247, 1, v248
	v_lshlrev_b32_e32 v248, 2, v248
	v_add_u32_e32 v249, 0x2c00, v248
	global_load_dwordx4 v[106:109], v248, s[62:63]
	global_load_dwordx4 v[110:113], v248, s[66:67]
	global_load_dwordx4 v[114:117], v248, s[68:69]
	global_load_dwordx4 v[118:121], v248, s[64:65]
	global_load_dwordx4 v[122:125], v249, s[62:63]
	global_load_dwordx4 v[126:129], v249, s[66:67]
	global_load_dwordx4 v[130:133], v249, s[68:69]
	global_load_dwordx4 v[134:137], v249, s[64:65]
	v_readlane_b32 s10, v254, 4
	v_readlane_b32 s11, v254, 5
	s_add_i32 s0, s78, s48
	s_mulk_i32 s0, 0x1600
	s_movk_i32 s29, 0x1600
	s_add_i32 s28, s93, -1
	v_add_u32_e32 v247, s0, v247
	v_mov_b32_e32 v202, 0
	v_mov_b32_e32 v203, 0
	v_and_b32_e32 v250, 7, v226
	v_lshlrev_b32_e32 v250, 3, v250
	v_add_u32_e32 v250, 0x27000, v250
	ds_write_b64 v250, v[202:203]
	s_mov_b64 exec, s[6:7]
	ds_write_b128 v238, v[166:169]
	ds_write_b128 v238, v[70:73] offset:16
	ds_write_b128 v238, v[162:165] offset:32
	ds_write_b128 v238, v[66:69] offset:48
	ds_write_b128 v239, v[102:105]
	ds_write_b128 v239, v[30:33] offset:16
	ds_write_b128 v239, v[98:101] offset:32
	ds_write_b128 v239, v[26:29] offset:48
	s_mov_b64 exec, s[4:5]
	ds_write_b128 v238, v[142:145] offset:1024
	ds_write_b128 v238, v[46:49] offset:1040
	ds_write_b128 v238, v[138:141] offset:1056
	ds_write_b128 v238, v[42:45] offset:1072
	ds_write_b128 v239, v[78:81] offset:1024
	ds_write_b128 v239, v[6:9] offset:1040
	ds_write_b128 v239, v[74:77] offset:1056
	ds_write_b128 v239, v[2:5] offset:1072
	s_mov_b64 exec, -1
	v_and_b32_e32 v250, 0xb80, v238
	v_lshlrev_b32_e32 v250, 3, v250
	v_bfe_u32 v251, v238, 6, 1
	v_lshl_add_u32 v250, v251, 3, v250
	v_lshl_add_u32 v250, v226, 4, v250
	v_add_u32_e32 v243, 0x20000, v250
	v_add_u32_e32 v244, 0xfffffff0, v243
	v_add_u32_e32 v250, 0xfffffc00, v238
	v_mov_b32_e32 v251, 0x27000
	v_cndmask_b32_e64 v245, v251, v250, s[74:75]
	v_add_u32_e32 v250, 0x800, v239
	v_cndmask_b32_e64 v246, v250, v251, s[74:75]
	v_cndmask_b32_e64 v38, 0, 1, s[6:7]
	v_cndmask_b32_e64 v39, 0, 1, s[4:5]
	v_cndmask_b32_e64 v198, v244, v245, s[6:7]
	v_add_u32_e32 v250, 0xc00, v238
	v_cndmask_b32_e64 v199, v244, v250, s[6:7]
	v_add_u32_e32 v251, 0x310, v243
	v_add_u32_e32 v250, 0x800, v238
	v_cndmask_b32_e64 v200, v251, v250, s[4:5]
	v_cndmask_b32_e64 v201, v251, v246, s[4:5]
	s_waitcnt lgkmcnt(0)
	s_barrier
	s_cmp_lt_i32 s48, 1
	s_cbranch_scc1 .Lec_edge
	s_add_i32 s0, s48, 0x100
	s_cmp_ge_i32 s0, s93
	s_cbranch_scc1 .Lec_edge
	v_cmp_le_i32_e64 s[12:13], s54, v227
	v_cmp_gt_i32_e32 vcc, s55, v227
	s_and_b64 s[12:13], s[12:13], vcc
	v_cmp_le_i32_e64 s[14:15], s54, v231
	v_cmp_gt_i32_e32 vcc, s55, v231
	s_and_b64 s[14:15], s[14:15], vcc
	v_cmp_le_i32_e64 s[16:17], s54, v232
	v_cmp_gt_i32_e32 vcc, s55, v232
	s_and_b64 s[16:17], s[16:17], vcc
	v_cmp_le_i32_e64 s[18:19], s54, v233
	v_cmp_gt_i32_e32 vcc, s55, v233
	s_and_b64 s[18:19], s[18:19], vcc
	v_cmp_le_i32_e64 s[20:21], s54, v234
	v_cmp_gt_i32_e32 vcc, s55, v234
	s_and_b64 s[20:21], s[20:21], vcc
	v_cmp_le_i32_e64 s[22:23], s54, v235
	v_cmp_gt_i32_e32 vcc, s55, v235
	s_and_b64 s[22:23], s[22:23], vcc
	v_cmp_le_i32_e64 s[24:25], s54, v236
	v_cmp_gt_i32_e32 vcc, s55, v236
	s_and_b64 s[24:25], s[24:25], vcc
	v_cmp_le_i32_e64 s[26:27], s54, v237
	v_cmp_gt_i32_e32 vcc, s55, v237
	s_and_b64 s[26:27], s[26:27], vcc
	ds_write_b64 v243, v[166:167]
	ds_write_b64 v243, v[158:159] offset:256
	ds_write_b64 v243, v[150:151] offset:512
	ds_write_b64 v243, v[142:143] offset:768
	v_mad_u32_u24 v250, v38, 0, v198
	ds_read_b64 v[170:171], v250
	ds_read_b64 v[178:179], v243 offset:16
	ds_read_b64 v[172:173], v244 offset:256
	ds_read_b64 v[180:181], v243 offset:272
	ds_read_b64 v[174:175], v244 offset:512
	ds_read_b64 v[194:195], v243 offset:528
	ds_read_b64 v[176:177], v244 offset:768
	v_mad_u32_u24 v251, v39, 0, v200
	ds_read_b64 v[196:197], v251
	s_waitcnt vmcnt(0)
	ds_write_b64 v243, v[168:169]
	ds_write_b64 v243, v[160:161] offset:256
	ds_write_b64 v243, v[152:153] offset:512
	ds_write_b64 v243, v[144:145] offset:768
	s_waitcnt lgkmcnt(10)
	v_pk_fma_f32 v[202:203], v[106:107], v[170:171], v[118:119]
	v_pk_fma_f32 v[166:167], v[166:167], v[110:111], v[202:203]
	v_pk_fma_f32 v[166:167], v[114:115], v[178:179], v[166:167]
	v_mad_u32_u24 v250, v38, 8, v198
	ds_read_b64 v[170:171], v250
	ds_read_b64 v[178:179], v243 offset:16
	s_waitcnt lgkmcnt(10)
	v_pk_fma_f32 v[202:203], v[106:107], v[172:173], v[118:119]
	v_pk_fma_f32 v[158:159], v[158:159], v[110:111], v[202:203]
	v_pk_fma_f32 v[158:159], v[114:115], v[180:181], v[158:159]
	ds_read_b64 v[172:173], v244 offset:256
	ds_read_b64 v[180:181], v243 offset:272
	s_waitcnt lgkmcnt(10)
	v_pk_fma_f32 v[202:203], v[106:107], v[174:175], v[118:119]
	v_pk_fma_f32 v[150:151], v[150:151], v[110:111], v[202:203]
	v_pk_fma_f32 v[150:151], v[114:115], v[194:195], v[150:151]
	ds_read_b64 v[174:175], v244 offset:512
	ds_read_b64 v[194:195], v243 offset:528
	s_waitcnt lgkmcnt(10)
	v_pk_fma_f32 v[202:203], v[106:107], v[176:177], v[118:119]
	v_pk_fma_f32 v[142:143], v[142:143], v[110:111], v[202:203]
	v_pk_fma_f32 v[142:143], v[114:115], v[196:197], v[142:143]
	ds_read_b64 v[176:177], v244 offset:768
	v_mad_u32_u24 v251, v39, 8, v200
	ds_read_b64 v[196:197], v251
	ds_write_b64 v243, v[162:163]
	ds_write_b64 v243, v[154:155] offset:256
	ds_write_b64 v243, v[146:147] offset:512
	ds_write_b64 v243, v[138:139] offset:768
	s_waitcnt lgkmcnt(10)
	v_pk_fma_f32 v[202:203], v[108:109], v[170:171], v[120:121]
	v_pk_fma_f32 v[168:169], v[168:169], v[112:113], v[202:203]
	v_pk_fma_f32 v[168:169], v[116:117], v[178:179], v[168:169]
	v_mad_u32_u24 v250, v38, 32, v198
	ds_read_b64 v[170:171], v250
	ds_read_b64 v[178:179], v243 offset:16
	s_waitcnt lgkmcnt(10)
; #define PG8_LAS __attribute__((address_space(3)))
; __device__ __forceinline__ unsigned cvt_pk_bf16(float lo, float hi) { unsigned r; asm volatile("v_cvt_pk_bf16_f32 %0, %1, %2" : "=v"(r) : "v"(lo), "v"(hi)); return r; }
;     __device__ __forceinline__ void operator()(const f32x4 (&acc)[2][2][4][2], const Unit& u, int wr, int wc, int fr, int fq) const {
;     ...
;                 for (int m = 0; m < 4; ++m) { const int r = 128 * ai + 64 * wr + 16 * m + fr, t = tstart + r;
;                     const bool upok = t >= 1, dnok = (t + 1) < T, store_ok = (r >= vlo) && (r < vhi) && (t < T);
;                     f32x4 res[2];
; #pragma unroll
;                     for (int bj = 0; bj < 2; ++bj) { const f32x4 cur = acc[ai][bj][m][n];
;                         f32x4 su = cur, sd = cur;
;                         if (m > 0) { if (fr == 15) su = acc[ai][bj][m > 0 ? m - 1 : 0][n]; }
;                         if (m < 3) { if (fr == 0) sd = acc[ai][bj][m < 3 ? m + 1 : 3][n]; }
;                         f32x4 up, dn;
;                         up[0] = dpp_ror1(su[0]); up[1] = dpp_ror1(su[1]); up[2] = dpp_ror1(su[2]); up[3] = dpp_ror1(su[3]);
;                         dn[0] = dpp_ror15(sd[0]); dn[1] = dpp_ror15(sd[1]); dn[2] = dpp_ror15(sd[2]); dn[3] = dpp_ror15(sd[3]);
;                         if (m == 0) { f32x4 halo = zero4; if (blk > 0) halo = *(const PG8_LAS f32x4*)(xb + (((((blk - 1) * 2 + 1) * 4 + wc) * 4 + fq) * 16 + (bj * 2 + n) * 4)); if (fr == 0) up = halo; }
;                         if (m == 3) { f32x4 halo = zero4; if (blk < 3) halo = *(const PG8_LAS f32x4*)(xb + (((((blk + 1) * 2 + 0) * 4 + wc) * 4 + fq) * 16 + (bj * 2 + n) * 4)); if (fr == 15) dn = halo; }
;                         if (edge) { if (!upok) up = zero4; if (!dnok) dn = zero4; }
;                         res[bj] = bb[bj] + w0[bj] * up + w1[bj] * cur + w2[bj] * dn; }
;                     if (store_ok) {
;                         float o[4];
; #pragma unroll
;                         for (int j = 0; j < 4; ++j) { const float gg = res[1][j]; o[j] = gg * __builtin_amdgcn_rcpf(1.f + __expf(-gg)) * res[0][j]; }
;                         u32x2 w; w.x = cvt_pk_bf16(o[0], o[1]); w.y = cvt_pk_bf16(o[2], o[3]);
;                         *(u32x2*)(ACT + (size_t)(seqrow + t) * 2816 + ch0 + 4 * n) = w; } } }
	v_pk_fma_f32 v[202:203], v[108:109], v[172:173], v[120:121]
	v_pk_fma_f32 v[160:161], v[160:161], v[112:113], v[202:203]
	v_pk_fma_f32 v[160:161], v[116:117], v[180:181], v[160:161]
	ds_read_b64 v[172:173], v244 offset:256
	ds_read_b64 v[180:181], v243 offset:272
	s_waitcnt lgkmcnt(10)
	v_pk_fma_f32 v[202:203], v[108:109], v[174:175], v[120:121]
	v_pk_fma_f32 v[152:153], v[152:153], v[112:113], v[202:203]
	v_pk_fma_f32 v[152:153], v[116:117], v[194:195], v[152:153]
	ds_read_b64 v[174:175], v244 offset:512
	ds_read_b64 v[194:195], v243 offset:528
	s_waitcnt lgkmcnt(10)
	v_pk_fma_f32 v[202:203], v[108:109], v[176:177], v[120:121]
	v_pk_fma_f32 v[144:145], v[144:145], v[112:113], v[202:203]
	v_pk_fma_f32 v[144:145], v[116:117], v[196:197], v[144:145]
	ds_read_b64 v[176:177], v244 offset:768
	v_mad_u32_u24 v251, v39, 32, v200
	ds_read_b64 v[196:197], v251
	ds_write_b64 v243, v[164:165]
	ds_write_b64 v243, v[156:157] offset:256
	ds_write_b64 v243, v[148:149] offset:512
	ds_write_b64 v243, v[140:141] offset:768
	s_waitcnt lgkmcnt(10)
	v_pk_fma_f32 v[202:203], v[122:123], v[170:171], v[134:135]
	v_pk_fma_f32 v[162:163], v[162:163], v[126:127], v[202:203]
	v_pk_fma_f32 v[162:163], v[130:131], v[178:179], v[162:163]
	v_mad_u32_u24 v250, v38, 40, v198
	ds_read_b64 v[170:171], v250
	ds_read_b64 v[178:179], v243 offset:16
	s_waitcnt lgkmcnt(10)
	v_pk_fma_f32 v[202:203], v[122:123], v[172:173], v[134:135]
	v_pk_fma_f32 v[154:155], v[154:155], v[126:127], v[202:203]
	v_pk_fma_f32 v[154:155], v[130:131], v[180:181], v[154:155]
	ds_read_b64 v[172:173], v244 offset:256
	ds_read_b64 v[180:181], v243 offset:272
	s_waitcnt lgkmcnt(10)
	v_pk_fma_f32 v[202:203], v[122:123], v[174:175], v[134:135]
	v_pk_fma_f32 v[146:147], v[146:147], v[126:127], v[202:203]
	v_pk_fma_f32 v[146:147], v[130:131], v[194:195], v[146:147]
	ds_read_b64 v[174:175], v244 offset:512
	ds_read_b64 v[194:195], v243 offset:528
	s_waitcnt lgkmcnt(10)
	v_pk_fma_f32 v[202:203], v[122:123], v[176:177], v[134:135]
	v_pk_fma_f32 v[138:139], v[138:139], v[126:127], v[202:203]
	v_pk_fma_f32 v[138:139], v[130:131], v[196:197], v[138:139]
	ds_read_b64 v[176:177], v244 offset:768
	v_mad_u32_u24 v251, v39, 40, v200
	ds_read_b64 v[196:197], v251
	ds_write_b64 v243, v[102:103]
	ds_write_b64 v243, v[94:95] offset:256
	ds_write_b64 v243, v[86:87] offset:512
	ds_write_b64 v243, v[78:79] offset:768
	s_waitcnt lgkmcnt(10)
	v_pk_fma_f32 v[202:203], v[124:125], v[170:171], v[136:137]
	v_pk_fma_f32 v[164:165], v[164:165], v[128:129], v[202:203]
	v_pk_fma_f32 v[164:165], v[132:133], v[178:179], v[164:165]
	v_mad_u32_u24 v250, v38, 0, v199
	ds_read_b64 v[170:171], v250
	ds_read_b64 v[178:179], v243 offset:16
	s_waitcnt lgkmcnt(10)
	v_pk_fma_f32 v[202:203], v[124:125], v[172:173], v[136:137]
	v_pk_fma_f32 v[156:157], v[156:157], v[128:129], v[202:203]
	v_pk_fma_f32 v[156:157], v[132:133], v[180:181], v[156:157]
	ds_read_b64 v[172:173], v244 offset:256
	ds_read_b64 v[180:181], v243 offset:272
	s_waitcnt lgkmcnt(10)
	v_pk_fma_f32 v[202:203], v[124:125], v[174:175], v[136:137]
	v_pk_fma_f32 v[148:149], v[148:149], v[128:129], v[202:203]
	v_pk_fma_f32 v[148:149], v[132:133], v[194:195], v[148:149]
	ds_read_b64 v[174:175], v244 offset:512
	ds_read_b64 v[194:195], v243 offset:528
	s_waitcnt lgkmcnt(10)
	v_pk_fma_f32 v[202:203], v[124:125], v[176:177], v[136:137]
	v_pk_fma_f32 v[140:141], v[140:141], v[128:129], v[202:203]
	v_pk_fma_f32 v[140:141], v[132:133], v[196:197], v[140:141]
	ds_read_b64 v[176:177], v244 offset:768
	v_mad_u32_u24 v251, v39, 0, v201
	ds_read_b64 v[196:197], v251
	v_mul_f32_e32 v208, 0xbfb8aa3b, v162
	v_mul_f32_e32 v209, 0xbfb8aa3b, v163
	v_mul_f32_e32 v210, 0xbfb8aa3b, v164
	v_mul_f32_e32 v211, 0xbfb8aa3b, v165
	v_exp_f32_e32 v208, v208
	v_exp_f32_e32 v209, v209
	v_exp_f32_e32 v210, v210
	v_exp_f32_e32 v211, v211
	v_add_f32_e32 v208, 1.0, v208
	v_add_f32_e32 v209, 1.0, v209
	v_add_f32_e32 v210, 1.0, v210
	v_add_f32_e32 v211, 1.0, v211
	v_rcp_f32_e32 v208, v208
	v_rcp_f32_e32 v209, v209
	v_rcp_f32_e32 v210, v210
	v_rcp_f32_e32 v211, v211
	v_mul_f32_e32 v162, v162, v208
	v_mul_f32_e32 v163, v163, v209
	v_mul_f32_e32 v164, v164, v210
	v_mul_f32_e32 v165, v165, v211
	v_mul_f32_e32 v162, v166, v162
	v_mul_f32_e32 v163, v167, v163
	v_mul_f32_e32 v164, v168, v164
	v_mul_f32_e32 v165, v169, v165
	v_cvt_pk_bf16_f32 v212, v162, v163
	v_cvt_pk_bf16_f32 v213, v164, v165
	v_mad_u32_u24 v221, v227, s29, v247
	s_and_saveexec_b64 s[30:31], s[12:13]
	global_store_dwordx2 v221, v[212:213], s[10:11]
	s_mov_b64 exec, s[30:31]
	v_mul_f32_e32 v208, 0xbfb8aa3b, v154
	v_mul_f32_e32 v209, 0xbfb8aa3b, v155
	v_mul_f32_e32 v210, 0xbfb8aa3b, v156
	v_mul_f32_e32 v211, 0xbfb8aa3b, v157
	v_exp_f32_e32 v208, v208
	v_exp_f32_e32 v209, v209
	v_exp_f32_e32 v210, v210
	v_exp_f32_e32 v211, v211
	v_add_f32_e32 v208, 1.0, v208
	v_add_f32_e32 v209, 1.0, v209
	v_add_f32_e32 v210, 1.0, v210
	v_add_f32_e32 v211, 1.0, v211
	v_rcp_f32_e32 v208, v208
	v_rcp_f32_e32 v209, v209
	v_rcp_f32_e32 v210, v210
	v_rcp_f32_e32 v211, v211
	v_mul_f32_e32 v154, v154, v208
	v_mul_f32_e32 v155, v155, v209
	v_mul_f32_e32 v156, v156, v210
	v_mul_f32_e32 v157, v157, v211
	v_mul_f32_e32 v154, v158, v154
	v_mul_f32_e32 v155, v159, v155
	v_mul_f32_e32 v156, v160, v156
	v_mul_f32_e32 v157, v161, v157
	v_cvt_pk_bf16_f32 v218, v154, v155
	v_cvt_pk_bf16_f32 v219, v156, v157
	v_mad_u32_u24 v40, v231, s29, v247
	s_and_saveexec_b64 s[30:31], s[14:15]
	global_store_dwordx2 v40, v[218:219], s[10:11]
	s_mov_b64 exec, s[30:31]
	v_mul_f32_e32 v208, 0xbfb8aa3b, v146
	v_mul_f32_e32 v209, 0xbfb8aa3b, v147
	v_mul_f32_e32 v210, 0xbfb8aa3b, v148
	v_mul_f32_e32 v211, 0xbfb8aa3b, v149
;     __device__ __forceinline__ void operator()(const f32x4 (&acc)[2][2][4][2], const Unit& u, int wr, int wc, int fr, int fq) const {
;     ...
;                 for (int bj = 0; bj < 2; ++bj) { const int col = bj * 2816 + ch0 + 4;
;                     w0[bj] = *(const f32x4*)(cw + col); w1[bj] = *(const f32x4*)(cw + 5632 + col); w2[bj] = *(const f32x4*)(cw + 11264 + col); bb[bj] = *(const f32x4*)(cb + col); } }
; #pragma unroll
;             for (int ai = 0; ai < 2; ++ai) { const int blk = ai * 2 + wr;
; #pragma unroll
;                 for (int m = 0; m < 4; ++m) { const int r = 128 * ai + 64 * wr + 16 * m + fr, t = tstart + r;
;                     const bool upok = t >= 1, dnok = (t + 1) < T, store_ok = (r >= vlo) && (r < vhi) && (t < T);
;                     f32x4 res[2];
; #pragma unroll
;                     for (int bj = 0; bj < 2; ++bj) { const f32x4 cur = acc[ai][bj][m][n];
;                         f32x4 su = cur, sd = cur;
;                         if (m > 0) { if (fr == 15) su = acc[ai][bj][m > 0 ? m - 1 : 0][n]; }
;                         if (m < 3) { if (fr == 0) sd = acc[ai][bj][m < 3 ? m + 1 : 3][n]; }
;                         f32x4 up, dn;
;                         up[0] = dpp_ror1(su[0]); up[1] = dpp_ror1(su[1]); up[2] = dpp_ror1(su[2]); up[3] = dpp_ror1(su[3]);
;                         dn[0] = dpp_ror15(sd[0]); dn[1] = dpp_ror15(sd[1]); dn[2] = dpp_ror15(sd[2]); dn[3] = dpp_ror15(sd[3]);
;                         if (m == 0) { f32x4 halo = zero4; if (blk > 0) halo = *(const PG8_LAS f32x4*)(xb + (((((blk - 1) * 2 + 1) * 4 + wc) * 4 + fq) * 16 + (bj * 2 + n) * 4)); if (fr == 0) up = halo; }
;                         if (m == 3) { f32x4 halo = zero4; if (blk < 3) halo = *(const PG8_LAS f32x4*)(xb + (((((blk + 1) * 2 + 0) * 4 + wc) * 4 + fq) * 16 + (bj * 2 + n) * 4)); if (fr == 15) dn = halo; }
;                         if (edge) { if (!upok) up = zero4; if (!dnok) dn = zero4; }
;                         res[bj] = bb[bj] + w0[bj] * up + w1[bj] * cur + w2[bj] * dn; }
;                     if (store_ok) {
;                         float o[4];
; #pragma unroll
;                         for (int j = 0; j < 4; ++j) { const float gg = res[1][j]; o[j] = gg * __builtin_amdgcn_rcpf(1.f + __expf(-gg)) * res[0][j]; }
;                         u32x2 w; w.x = cvt_pk_bf16(o[0], o[1]); w.y = cvt_pk_bf16(o[2], o[3]);
	v_exp_f32_e32 v208, v208
	v_exp_f32_e32 v209, v209
	v_exp_f32_e32 v210, v210
	v_exp_f32_e32 v211, v211
	v_add_f32_e32 v208, 1.0, v208
	v_add_f32_e32 v209, 1.0, v209
	v_add_f32_e32 v210, 1.0, v210
	v_add_f32_e32 v211, 1.0, v211
	v_rcp_f32_e32 v208, v208
	v_rcp_f32_e32 v209, v209
	v_rcp_f32_e32 v210, v210
	v_rcp_f32_e32 v211, v211
	v_mul_f32_e32 v146, v146, v208
	v_mul_f32_e32 v147, v147, v209
	v_mul_f32_e32 v148, v148, v210
	v_mul_f32_e32 v149, v149, v211
	v_mul_f32_e32 v146, v150, v146
	v_mul_f32_e32 v147, v151, v147
	v_mul_f32_e32 v148, v152, v148
	v_mul_f32_e32 v149, v153, v149
	v_cvt_pk_bf16_f32 v212, v146, v147
	v_cvt_pk_bf16_f32 v213, v148, v149
	v_mad_u32_u24 v221, v232, s29, v247
	s_and_saveexec_b64 s[30:31], s[16:17]
	global_store_dwordx2 v221, v[212:213], s[10:11]
	s_mov_b64 exec, s[30:31]
	v_mul_f32_e32 v208, 0xbfb8aa3b, v138
	v_mul_f32_e32 v209, 0xbfb8aa3b, v139
	v_mul_f32_e32 v210, 0xbfb8aa3b, v140
	v_mul_f32_e32 v211, 0xbfb8aa3b, v141
	v_exp_f32_e32 v208, v208
	v_exp_f32_e32 v209, v209
	v_exp_f32_e32 v210, v210
	v_exp_f32_e32 v211, v211
	v_add_f32_e32 v208, 1.0, v208
	v_add_f32_e32 v209, 1.0, v209
	v_add_f32_e32 v210, 1.0, v210
	v_add_f32_e32 v211, 1.0, v211
	v_rcp_f32_e32 v208, v208
	v_rcp_f32_e32 v209, v209
	v_rcp_f32_e32 v210, v210
	v_rcp_f32_e32 v211, v211
	v_mul_f32_e32 v138, v138, v208
	v_mul_f32_e32 v139, v139, v209
	v_mul_f32_e32 v140, v140, v210
	v_mul_f32_e32 v141, v141, v211
	v_mul_f32_e32 v138, v142, v138
	v_mul_f32_e32 v139, v143, v139
	v_mul_f32_e32 v140, v144, v140
	v_mul_f32_e32 v141, v145, v141
	v_cvt_pk_bf16_f32 v218, v138, v139
	v_cvt_pk_bf16_f32 v219, v140, v141
	v_mad_u32_u24 v40, v233, s29, v247
	s_and_saveexec_b64 s[30:31], s[18:19]
	global_store_dwordx2 v40, v[218:219], s[10:11]
	s_mov_b64 exec, s[30:31]
	global_load_dwordx4 v[138:141], v248, s[62:63] offset:16
	global_load_dwordx4 v[142:145], v248, s[66:67] offset:16
	global_load_dwordx4 v[146:149], v248, s[68:69] offset:16
	global_load_dwordx4 v[150:153], v248, s[64:65] offset:16
	global_load_dwordx4 v[154:157], v249, s[62:63] offset:16
	global_load_dwordx4 v[158:161], v249, s[66:67] offset:16
	global_load_dwordx4 v[162:165], v249, s[68:69] offset:16
	global_load_dwordx4 v[166:169], v249, s[64:65] offset:16
	ds_write_b64 v243, v[104:105]
	ds_write_b64 v243, v[96:97] offset:256
	ds_write_b64 v243, v[88:89] offset:512
	ds_write_b64 v243, v[80:81] offset:768
	s_waitcnt lgkmcnt(10)
	v_pk_fma_f32 v[202:203], v[106:107], v[170:171], v[118:119]
	v_pk_fma_f32 v[102:103], v[102:103], v[110:111], v[202:203]
	v_pk_fma_f32 v[102:103], v[114:115], v[178:179], v[102:103]
	v_mad_u32_u24 v250, v38, 8, v199
	ds_read_b64 v[170:171], v250
	ds_read_b64 v[178:179], v243 offset:16
	s_waitcnt lgkmcnt(10)
	v_pk_fma_f32 v[202:203], v[106:107], v[172:173], v[118:119]
	v_pk_fma_f32 v[94:95], v[94:95], v[110:111], v[202:203]
	v_pk_fma_f32 v[94:95], v[114:115], v[180:181], v[94:95]
	ds_read_b64 v[172:173], v244 offset:256
	ds_read_b64 v[180:181], v243 offset:272
	s_waitcnt lgkmcnt(10)
	v_pk_fma_f32 v[202:203], v[106:107], v[174:175], v[118:119]
	v_pk_fma_f32 v[86:87], v[86:87], v[110:111], v[202:203]
	v_pk_fma_f32 v[86:87], v[114:115], v[194:195], v[86:87]
	ds_read_b64 v[174:175], v244 offset:512
	ds_read_b64 v[194:195], v243 offset:528
	s_waitcnt lgkmcnt(10)
	v_pk_fma_f32 v[202:203], v[106:107], v[176:177], v[118:119]
	v_pk_fma_f32 v[78:79], v[78:79], v[110:111], v[202:203]
	v_pk_fma_f32 v[78:79], v[114:115], v[196:197], v[78:79]
	ds_read_b64 v[176:177], v244 offset:768
	v_mad_u32_u24 v251, v39, 8, v201
	ds_read_b64 v[196:197], v251
	ds_write_b64 v243, v[98:99]
	ds_write_b64 v243, v[90:91] offset:256
	ds_write_b64 v243, v[82:83] offset:512
	ds_write_b64 v243, v[74:75] offset:768
	s_waitcnt lgkmcnt(10)
	v_pk_fma_f32 v[202:203], v[108:109], v[170:171], v[120:121]
	v_pk_fma_f32 v[104:105], v[104:105], v[112:113], v[202:203]
	v_pk_fma_f32 v[104:105], v[116:117], v[178:179], v[104:105]
	v_mad_u32_u24 v250, v38, 32, v199
	ds_read_b64 v[170:171], v250
	ds_read_b64 v[178:179], v243 offset:16
	s_waitcnt lgkmcnt(10)
	v_pk_fma_f32 v[202:203], v[108:109], v[172:173], v[120:121]
	v_pk_fma_f32 v[96:97], v[96:97], v[112:113], v[202:203]
	v_pk_fma_f32 v[96:97], v[116:117], v[180:181], v[96:97]
	ds_read_b64 v[172:173], v244 offset:256
	ds_read_b64 v[180:181], v243 offset:272
	s_waitcnt lgkmcnt(10)
	v_pk_fma_f32 v[202:203], v[108:109], v[174:175], v[120:121]
	v_pk_fma_f32 v[88:89], v[88:89], v[112:113], v[202:203]
	v_pk_fma_f32 v[88:89], v[116:117], v[194:195], v[88:89]
	ds_read_b64 v[174:175], v244 offset:512
	ds_read_b64 v[194:195], v243 offset:528
	s_waitcnt lgkmcnt(10)
	v_pk_fma_f32 v[202:203], v[108:109], v[176:177], v[120:121]
	v_pk_fma_f32 v[80:81], v[80:81], v[112:113], v[202:203]
	v_pk_fma_f32 v[80:81], v[116:117], v[196:197], v[80:81]
	ds_read_b64 v[176:177], v244 offset:768
	v_mad_u32_u24 v251, v39, 32, v201
	ds_read_b64 v[196:197], v251
	ds_write_b64 v243, v[100:101]
	ds_write_b64 v243, v[92:93] offset:256
	ds_write_b64 v243, v[84:85] offset:512
	ds_write_b64 v243, v[76:77] offset:768
	s_waitcnt lgkmcnt(10)
	v_pk_fma_f32 v[202:203], v[122:123], v[170:171], v[134:135]
	v_pk_fma_f32 v[98:99], v[98:99], v[126:127], v[202:203]
	v_pk_fma_f32 v[98:99], v[130:131], v[178:179], v[98:99]
	v_mad_u32_u24 v250, v38, 40, v199
	ds_read_b64 v[170:171], v250
	ds_read_b64 v[178:179], v243 offset:16
	s_waitcnt lgkmcnt(10)
	v_pk_fma_f32 v[202:203], v[122:123], v[172:173], v[134:135]
	v_pk_fma_f32 v[90:91], v[90:91], v[126:127], v[202:203]
	v_pk_fma_f32 v[90:91], v[130:131], v[180:181], v[90:91]
	ds_read_b64 v[172:173], v244 offset:256
	ds_read_b64 v[180:181], v243 offset:272
	s_waitcnt lgkmcnt(10)
; #define PG8_LAS __attribute__((address_space(3)))
; __device__ __forceinline__ unsigned cvt_pk_bf16(float lo, float hi) { unsigned r; asm volatile("v_cvt_pk_bf16_f32 %0, %1, %2" : "=v"(r) : "v"(lo), "v"(hi)); return r; }
;     __device__ __forceinline__ void operator()(const f32x4 (&acc)[2][2][4][2], const Unit& u, int wr, int wc, int fr, int fq) const {
;     ...
;                 for (int m = 0; m < 4; ++m) { const int r = 128 * ai + 64 * wr + 16 * m + fr, t = tstart + r;
;                     const bool upok = t >= 1, dnok = (t + 1) < T, store_ok = (r >= vlo) && (r < vhi) && (t < T);
;                     f32x4 res[2];
; #pragma unroll
;                     for (int bj = 0; bj < 2; ++bj) { const f32x4 cur = acc[ai][bj][m][n];
;                         f32x4 su = cur, sd = cur;
;                         if (m > 0) { if (fr == 15) su = acc[ai][bj][m > 0 ? m - 1 : 0][n]; }
;                         if (m < 3) { if (fr == 0) sd = acc[ai][bj][m < 3 ? m + 1 : 3][n]; }
;                         f32x4 up, dn;
;                         up[0] = dpp_ror1(su[0]); up[1] = dpp_ror1(su[1]); up[2] = dpp_ror1(su[2]); up[3] = dpp_ror1(su[3]);
;                         dn[0] = dpp_ror15(sd[0]); dn[1] = dpp_ror15(sd[1]); dn[2] = dpp_ror15(sd[2]); dn[3] = dpp_ror15(sd[3]);
;                         if (m == 0) { f32x4 halo = zero4; if (blk > 0) halo = *(const PG8_LAS f32x4*)(xb + (((((blk - 1) * 2 + 1) * 4 + wc) * 4 + fq) * 16 + (bj * 2 + n) * 4)); if (fr == 0) up = halo; }
;                         if (m == 3) { f32x4 halo = zero4; if (blk < 3) halo = *(const PG8_LAS f32x4*)(xb + (((((blk + 1) * 2 + 0) * 4 + wc) * 4 + fq) * 16 + (bj * 2 + n) * 4)); if (fr == 15) dn = halo; }
;                         if (edge) { if (!upok) up = zero4; if (!dnok) dn = zero4; }
;                         res[bj] = bb[bj] + w0[bj] * up + w1[bj] * cur + w2[bj] * dn; }
;                     if (store_ok) {
;                         float o[4];
; #pragma unroll
;                         for (int j = 0; j < 4; ++j) { const float gg = res[1][j]; o[j] = gg * __builtin_amdgcn_rcpf(1.f + __expf(-gg)) * res[0][j]; }
;                         u32x2 w; w.x = cvt_pk_bf16(o[0], o[1]); w.y = cvt_pk_bf16(o[2], o[3]);
;                         *(u32x2*)(ACT + (size_t)(seqrow + t) * 2816 + ch0 + 4 * n) = w; } } }
	v_pk_fma_f32 v[202:203], v[122:123], v[174:175], v[134:135]
	v_pk_fma_f32 v[82:83], v[82:83], v[126:127], v[202:203]
	v_pk_fma_f32 v[82:83], v[130:131], v[194:195], v[82:83]
	ds_read_b64 v[174:175], v244 offset:512
	ds_read_b64 v[194:195], v243 offset:528
	s_waitcnt lgkmcnt(10)
	v_pk_fma_f32 v[202:203], v[122:123], v[176:177], v[134:135]
	v_pk_fma_f32 v[74:75], v[74:75], v[126:127], v[202:203]
	v_pk_fma_f32 v[74:75], v[130:131], v[196:197], v[74:75]
	ds_read_b64 v[176:177], v244 offset:768
	v_mad_u32_u24 v251, v39, 40, v201
	ds_read_b64 v[196:197], v251
	ds_write_b64 v243, v[70:71]
	ds_write_b64 v243, v[62:63] offset:256
	ds_write_b64 v243, v[54:55] offset:512
	ds_write_b64 v243, v[46:47] offset:768
	s_waitcnt lgkmcnt(10)
	v_pk_fma_f32 v[202:203], v[124:125], v[170:171], v[136:137]
	v_pk_fma_f32 v[100:101], v[100:101], v[128:129], v[202:203]
	v_pk_fma_f32 v[100:101], v[132:133], v[178:179], v[100:101]
	v_mad_u32_u24 v250, v38, 16, v198
	ds_read_b64 v[170:171], v250
	ds_read_b64 v[178:179], v243 offset:16
	s_waitcnt lgkmcnt(10)
	v_pk_fma_f32 v[202:203], v[124:125], v[172:173], v[136:137]
	v_pk_fma_f32 v[92:93], v[92:93], v[128:129], v[202:203]
	v_pk_fma_f32 v[92:93], v[132:133], v[180:181], v[92:93]
	ds_read_b64 v[172:173], v244 offset:256
	ds_read_b64 v[180:181], v243 offset:272
	s_waitcnt lgkmcnt(10)
	v_pk_fma_f32 v[202:203], v[124:125], v[174:175], v[136:137]
	v_pk_fma_f32 v[84:85], v[84:85], v[128:129], v[202:203]
	v_pk_fma_f32 v[84:85], v[132:133], v[194:195], v[84:85]
	ds_read_b64 v[174:175], v244 offset:512
	ds_read_b64 v[194:195], v243 offset:528
	s_waitcnt lgkmcnt(10)
	v_pk_fma_f32 v[202:203], v[124:125], v[176:177], v[136:137]
	v_pk_fma_f32 v[76:77], v[76:77], v[128:129], v[202:203]
	v_pk_fma_f32 v[76:77], v[132:133], v[196:197], v[76:77]
	ds_read_b64 v[176:177], v244 offset:768
	v_mad_u32_u24 v251, v39, 16, v200
	ds_read_b64 v[196:197], v251
	v_mul_f32_e32 v208, 0xbfb8aa3b, v98
	v_mul_f32_e32 v209, 0xbfb8aa3b, v99
	v_mul_f32_e32 v210, 0xbfb8aa3b, v100
	v_mul_f32_e32 v211, 0xbfb8aa3b, v101
	v_exp_f32_e32 v208, v208
	v_exp_f32_e32 v209, v209
	v_exp_f32_e32 v210, v210
	v_exp_f32_e32 v211, v211
	v_add_f32_e32 v208, 1.0, v208
	v_add_f32_e32 v209, 1.0, v209
	v_add_f32_e32 v210, 1.0, v210
	v_add_f32_e32 v211, 1.0, v211
	v_rcp_f32_e32 v208, v208
	v_rcp_f32_e32 v209, v209
	v_rcp_f32_e32 v210, v210
	v_rcp_f32_e32 v211, v211
	v_mul_f32_e32 v98, v98, v208
	v_mul_f32_e32 v99, v99, v209
	v_mul_f32_e32 v100, v100, v210
	v_mul_f32_e32 v101, v101, v211
	v_mul_f32_e32 v98, v102, v98
	v_mul_f32_e32 v99, v103, v99
	v_mul_f32_e32 v100, v104, v100
	v_mul_f32_e32 v101, v105, v101
	v_cvt_pk_bf16_f32 v212, v98, v99
	v_cvt_pk_bf16_f32 v213, v100, v101
	v_mad_u32_u24 v221, v234, s29, v247
	s_and_saveexec_b64 s[30:31], s[20:21]
	global_store_dwordx2 v221, v[212:213], s[10:11]
	s_mov_b64 exec, s[30:31]
	v_mul_f32_e32 v208, 0xbfb8aa3b, v90
	v_mul_f32_e32 v209, 0xbfb8aa3b, v91
	v_mul_f32_e32 v210, 0xbfb8aa3b, v92
	v_mul_f32_e32 v211, 0xbfb8aa3b, v93
	v_exp_f32_e32 v208, v208
	v_exp_f32_e32 v209, v209
	v_exp_f32_e32 v210, v210
	v_exp_f32_e32 v211, v211
	v_add_f32_e32 v208, 1.0, v208
	v_add_f32_e32 v209, 1.0, v209
	v_add_f32_e32 v210, 1.0, v210
	v_add_f32_e32 v211, 1.0, v211
	v_rcp_f32_e32 v208, v208
	v_rcp_f32_e32 v209, v209
	v_rcp_f32_e32 v210, v210
	v_rcp_f32_e32 v211, v211
	v_mul_f32_e32 v90, v90, v208
	v_mul_f32_e32 v91, v91, v209
	v_mul_f32_e32 v92, v92, v210
	v_mul_f32_e32 v93, v93, v211
	v_mul_f32_e32 v90, v94, v90
	v_mul_f32_e32 v91, v95, v91
	v_mul_f32_e32 v92, v96, v92
	v_mul_f32_e32 v93, v97, v93
	v_cvt_pk_bf16_f32 v218, v90, v91
	v_cvt_pk_bf16_f32 v219, v92, v93
	v_mad_u32_u24 v40, v235, s29, v247
	s_and_saveexec_b64 s[30:31], s[22:23]
	global_store_dwordx2 v40, v[218:219], s[10:11]
	s_mov_b64 exec, s[30:31]
	v_mul_f32_e32 v208, 0xbfb8aa3b, v82
	v_mul_f32_e32 v209, 0xbfb8aa3b, v83
	v_mul_f32_e32 v210, 0xbfb8aa3b, v84
	v_mul_f32_e32 v211, 0xbfb8aa3b, v85
	v_exp_f32_e32 v208, v208
	v_exp_f32_e32 v209, v209
	v_exp_f32_e32 v210, v210
	v_exp_f32_e32 v211, v211
	v_add_f32_e32 v208, 1.0, v208
	v_add_f32_e32 v209, 1.0, v209
	v_add_f32_e32 v210, 1.0, v210
	v_add_f32_e32 v211, 1.0, v211
	v_rcp_f32_e32 v208, v208
	v_rcp_f32_e32 v209, v209
	v_rcp_f32_e32 v210, v210
	v_rcp_f32_e32 v211, v211
	v_mul_f32_e32 v82, v82, v208
	v_mul_f32_e32 v83, v83, v209
	v_mul_f32_e32 v84, v84, v210
	v_mul_f32_e32 v85, v85, v211
	v_mul_f32_e32 v82, v86, v82
	v_mul_f32_e32 v83, v87, v83
	v_mul_f32_e32 v84, v88, v84
	v_mul_f32_e32 v85, v89, v85
	v_cvt_pk_bf16_f32 v212, v82, v83
	v_cvt_pk_bf16_f32 v213, v84, v85
	v_mad_u32_u24 v221, v236, s29, v247
	s_and_saveexec_b64 s[30:31], s[24:25]
	global_store_dwordx2 v221, v[212:213], s[10:11]
	s_mov_b64 exec, s[30:31]
	v_mul_f32_e32 v208, 0xbfb8aa3b, v74
	v_mul_f32_e32 v209, 0xbfb8aa3b, v75
	v_mul_f32_e32 v210, 0xbfb8aa3b, v76
	v_mul_f32_e32 v211, 0xbfb8aa3b, v77
	v_exp_f32_e32 v208, v208
	v_exp_f32_e32 v209, v209
	v_exp_f32_e32 v210, v210
	v_exp_f32_e32 v211, v211
	v_add_f32_e32 v208, 1.0, v208
	v_add_f32_e32 v209, 1.0, v209
	v_add_f32_e32 v210, 1.0, v210
	v_add_f32_e32 v211, 1.0, v211
	v_rcp_f32_e32 v208, v208
	v_rcp_f32_e32 v209, v209
	v_rcp_f32_e32 v210, v210
	v_rcp_f32_e32 v211, v211
	v_mul_f32_e32 v74, v74, v208
	v_mul_f32_e32 v75, v75, v209
	v_mul_f32_e32 v76, v76, v210
	v_mul_f32_e32 v77, v77, v211
	v_mul_f32_e32 v74, v78, v74
	v_mul_f32_e32 v75, v79, v75
	v_mul_f32_e32 v76, v80, v76
	v_mul_f32_e32 v77, v81, v77
	v_cvt_pk_bf16_f32 v218, v74, v75
	v_cvt_pk_bf16_f32 v219, v76, v77
	v_mad_u32_u24 v40, v237, s29, v247
	s_and_saveexec_b64 s[30:31], s[26:27]
	global_store_dwordx2 v40, v[218:219], s[10:11]
	s_mov_b64 exec, s[30:31]
	s_waitcnt vmcnt(4)
; #define PG8_LAS __attribute__((address_space(3)))
; __device__ __forceinline__ float dpp_ror1(float v) { return __builtin_bit_cast(float, __builtin_amdgcn_update_dpp(0, __builtin_bit_cast(int, v), 0x121, 0xf, 0xf, false)); }
; __device__ __forceinline__ float dpp_ror15(float v) { return __builtin_bit_cast(float, __builtin_amdgcn_update_dpp(0, __builtin_bit_cast(int, v), 0x12F, 0xf, 0xf, false)); }
;     __device__ __forceinline__ void operator()(const f32x4 (&acc)[2][2][4][2], const Unit& u, int wr, int wc, int fr, int fq) const {
;     ...
;                 for (int m = 0; m < 4; ++m) { const int r = 128 * ai + 64 * wr + 16 * m + fr, t = tstart + r;
;                     const bool upok = t >= 1, dnok = (t + 1) < T, store_ok = (r >= vlo) && (r < vhi) && (t < T);
;                     f32x4 res[2];
; #pragma unroll
;                     for (int bj = 0; bj < 2; ++bj) { const f32x4 cur = acc[ai][bj][m][n];
;                         f32x4 su = cur, sd = cur;
;                         if (m > 0) { if (fr == 15) su = acc[ai][bj][m > 0 ? m - 1 : 0][n]; }
;                         if (m < 3) { if (fr == 0) sd = acc[ai][bj][m < 3 ? m + 1 : 3][n]; }
;                         f32x4 up, dn;
;                         up[0] = dpp_ror1(su[0]); up[1] = dpp_ror1(su[1]); up[2] = dpp_ror1(su[2]); up[3] = dpp_ror1(su[3]);
;                         dn[0] = dpp_ror15(sd[0]); dn[1] = dpp_ror15(sd[1]); dn[2] = dpp_ror15(sd[2]); dn[3] = dpp_ror15(sd[3]);
;                         if (m == 0) { f32x4 halo = zero4; if (blk > 0) halo = *(const PG8_LAS f32x4*)(xb + (((((blk - 1) * 2 + 1) * 4 + wc) * 4 + fq) * 16 + (bj * 2 + n) * 4)); if (fr == 0) up = halo; }
;                         if (m == 3) { f32x4 halo = zero4; if (blk < 3) halo = *(const PG8_LAS f32x4*)(xb + (((((blk + 1) * 2 + 0) * 4 + wc) * 4 + fq) * 16 + (bj * 2 + n) * 4)); if (fr == 15) dn = halo; }
;                         if (edge) { if (!upok) up = zero4; if (!dnok) dn = zero4; }
;                         res[bj] = bb[bj] + w0[bj] * up + w1[bj] * cur + w2[bj] * dn; }
	ds_write_b64 v243, v[72:73]
	ds_write_b64 v243, v[64:65] offset:256
	ds_write_b64 v243, v[56:57] offset:512
	ds_write_b64 v243, v[48:49] offset:768
	s_waitcnt lgkmcnt(10)
	v_pk_fma_f32 v[202:203], v[138:139], v[170:171], v[150:151]
	v_pk_fma_f32 v[70:71], v[70:71], v[142:143], v[202:203]
	v_pk_fma_f32 v[70:71], v[146:147], v[178:179], v[70:71]
	v_mad_u32_u24 v250, v38, 24, v198
	ds_read_b64 v[170:171], v250
	ds_read_b64 v[178:179], v243 offset:16
	s_waitcnt lgkmcnt(10)
	v_pk_fma_f32 v[202:203], v[138:139], v[172:173], v[150:151]
	v_pk_fma_f32 v[62:63], v[62:63], v[142:143], v[202:203]
	v_pk_fma_f32 v[62:63], v[146:147], v[180:181], v[62:63]
	ds_read_b64 v[172:173], v244 offset:256
	ds_read_b64 v[180:181], v243 offset:272
	s_waitcnt lgkmcnt(10)
	v_pk_fma_f32 v[202:203], v[138:139], v[174:175], v[150:151]
	v_pk_fma_f32 v[54:55], v[54:55], v[142:143], v[202:203]
	v_pk_fma_f32 v[54:55], v[146:147], v[194:195], v[54:55]
	ds_read_b64 v[174:175], v244 offset:512
	ds_read_b64 v[194:195], v243 offset:528
	s_waitcnt lgkmcnt(10)
	v_pk_fma_f32 v[202:203], v[138:139], v[176:177], v[150:151]
	v_pk_fma_f32 v[46:47], v[46:47], v[142:143], v[202:203]
	v_pk_fma_f32 v[46:47], v[146:147], v[196:197], v[46:47]
	ds_read_b64 v[176:177], v244 offset:768
	v_mad_u32_u24 v251, v39, 24, v200
	ds_read_b64 v[196:197], v251
	ds_write_b64 v243, v[66:67]
	ds_write_b64 v243, v[58:59] offset:256
	ds_write_b64 v243, v[50:51] offset:512
	ds_write_b64 v243, v[42:43] offset:768
	s_waitcnt lgkmcnt(10)
	v_pk_fma_f32 v[202:203], v[140:141], v[170:171], v[152:153]
	v_pk_fma_f32 v[72:73], v[72:73], v[144:145], v[202:203]
	v_pk_fma_f32 v[72:73], v[148:149], v[178:179], v[72:73]
	v_mad_u32_u24 v250, v38, 48, v198
	ds_read_b64 v[170:171], v250
	ds_read_b64 v[178:179], v243 offset:16
	s_waitcnt lgkmcnt(10)
	v_pk_fma_f32 v[202:203], v[140:141], v[172:173], v[152:153]
	v_pk_fma_f32 v[64:65], v[64:65], v[144:145], v[202:203]
	v_pk_fma_f32 v[64:65], v[148:149], v[180:181], v[64:65]
	ds_read_b64 v[172:173], v244 offset:256
	ds_read_b64 v[180:181], v243 offset:272
	s_waitcnt lgkmcnt(10)
	v_pk_fma_f32 v[202:203], v[140:141], v[174:175], v[152:153]
	v_pk_fma_f32 v[56:57], v[56:57], v[144:145], v[202:203]
	v_pk_fma_f32 v[56:57], v[148:149], v[194:195], v[56:57]
	ds_read_b64 v[174:175], v244 offset:512
	ds_read_b64 v[194:195], v243 offset:528
	s_waitcnt lgkmcnt(10)
	v_pk_fma_f32 v[202:203], v[140:141], v[176:177], v[152:153]
	v_pk_fma_f32 v[48:49], v[48:49], v[144:145], v[202:203]
	v_pk_fma_f32 v[48:49], v[148:149], v[196:197], v[48:49]
	ds_read_b64 v[176:177], v244 offset:768
	v_mad_u32_u24 v251, v39, 48, v200
	ds_read_b64 v[196:197], v251
	ds_write_b64 v243, v[68:69]
	ds_write_b64 v243, v[60:61] offset:256
	ds_write_b64 v243, v[52:53] offset:512
	ds_write_b64 v243, v[44:45] offset:768
	s_waitcnt lgkmcnt(10)
	v_pk_fma_f32 v[202:203], v[154:155], v[170:171], v[166:167]
	v_pk_fma_f32 v[66:67], v[66:67], v[158:159], v[202:203]
	v_pk_fma_f32 v[66:67], v[162:163], v[178:179], v[66:67]
	v_mad_u32_u24 v250, v38, 56, v198
	ds_read_b64 v[170:171], v250
	ds_read_b64 v[178:179], v243 offset:16
	s_waitcnt lgkmcnt(10)
	v_pk_fma_f32 v[202:203], v[154:155], v[172:173], v[166:167]
	v_pk_fma_f32 v[58:59], v[58:59], v[158:159], v[202:203]
	v_pk_fma_f32 v[58:59], v[162:163], v[180:181], v[58:59]
	ds_read_b64 v[172:173], v244 offset:256
	ds_read_b64 v[180:181], v243 offset:272
	s_waitcnt lgkmcnt(10)
	v_pk_fma_f32 v[202:203], v[154:155], v[174:175], v[166:167]
	v_pk_fma_f32 v[50:51], v[50:51], v[158:159], v[202:203]
	v_pk_fma_f32 v[50:51], v[162:163], v[194:195], v[50:51]
	ds_read_b64 v[174:175], v244 offset:512
	ds_read_b64 v[194:195], v243 offset:528
	s_waitcnt lgkmcnt(10)
	v_pk_fma_f32 v[202:203], v[154:155], v[176:177], v[166:167]
	v_pk_fma_f32 v[42:43], v[42:43], v[158:159], v[202:203]
	v_pk_fma_f32 v[42:43], v[162:163], v[196:197], v[42:43]
	ds_read_b64 v[176:177], v244 offset:768
	v_mad_u32_u24 v251, v39, 56, v200
	ds_read_b64 v[196:197], v251
	ds_write_b64 v243, v[30:31]
	ds_write_b64 v243, v[22:23] offset:256
	ds_write_b64 v243, v[14:15] offset:512
	ds_write_b64 v243, v[6:7] offset:768
	s_waitcnt lgkmcnt(10)
	v_pk_fma_f32 v[202:203], v[156:157], v[170:171], v[168:169]
	v_pk_fma_f32 v[68:69], v[68:69], v[160:161], v[202:203]
	v_pk_fma_f32 v[68:69], v[164:165], v[178:179], v[68:69]
	v_mad_u32_u24 v250, v38, 16, v199
	ds_read_b64 v[170:171], v250
	ds_read_b64 v[178:179], v243 offset:16
	s_waitcnt lgkmcnt(10)
	v_pk_fma_f32 v[202:203], v[156:157], v[172:173], v[168:169]
	v_pk_fma_f32 v[60:61], v[60:61], v[160:161], v[202:203]
	v_pk_fma_f32 v[60:61], v[164:165], v[180:181], v[60:61]
	ds_read_b64 v[172:173], v244 offset:256
	ds_read_b64 v[180:181], v243 offset:272
	s_waitcnt lgkmcnt(10)
	v_pk_fma_f32 v[202:203], v[156:157], v[174:175], v[168:169]
	v_pk_fma_f32 v[52:53], v[52:53], v[160:161], v[202:203]
	v_pk_fma_f32 v[52:53], v[164:165], v[194:195], v[52:53]
	ds_read_b64 v[174:175], v244 offset:512
	ds_read_b64 v[194:195], v243 offset:528
	s_waitcnt lgkmcnt(10)
; #define PG8_LAS __attribute__((address_space(3)))
; __device__ __forceinline__ unsigned cvt_pk_bf16(float lo, float hi) { unsigned r; asm volatile("v_cvt_pk_bf16_f32 %0, %1, %2" : "=v"(r) : "v"(lo), "v"(hi)); return r; }
;     __device__ __forceinline__ void operator()(const f32x4 (&acc)[2][2][4][2], const Unit& u, int wr, int wc, int fr, int fq) const {
;     ...
;                 for (int m = 0; m < 4; ++m) { const int r = 128 * ai + 64 * wr + 16 * m + fr, t = tstart + r;
;                     const bool upok = t >= 1, dnok = (t + 1) < T, store_ok = (r >= vlo) && (r < vhi) && (t < T);
;                     f32x4 res[2];
; #pragma unroll
;                     for (int bj = 0; bj < 2; ++bj) { const f32x4 cur = acc[ai][bj][m][n];
;                         f32x4 su = cur, sd = cur;
;                         if (m > 0) { if (fr == 15) su = acc[ai][bj][m > 0 ? m - 1 : 0][n]; }
;                         if (m < 3) { if (fr == 0) sd = acc[ai][bj][m < 3 ? m + 1 : 3][n]; }
;                         f32x4 up, dn;
;                         up[0] = dpp_ror1(su[0]); up[1] = dpp_ror1(su[1]); up[2] = dpp_ror1(su[2]); up[3] = dpp_ror1(su[3]);
;                         dn[0] = dpp_ror15(sd[0]); dn[1] = dpp_ror15(sd[1]); dn[2] = dpp_ror15(sd[2]); dn[3] = dpp_ror15(sd[3]);
;                         if (m == 0) { f32x4 halo = zero4; if (blk > 0) halo = *(const PG8_LAS f32x4*)(xb + (((((blk - 1) * 2 + 1) * 4 + wc) * 4 + fq) * 16 + (bj * 2 + n) * 4)); if (fr == 0) up = halo; }
;                         if (m == 3) { f32x4 halo = zero4; if (blk < 3) halo = *(const PG8_LAS f32x4*)(xb + (((((blk + 1) * 2 + 0) * 4 + wc) * 4 + fq) * 16 + (bj * 2 + n) * 4)); if (fr == 15) dn = halo; }
;                         if (edge) { if (!upok) up = zero4; if (!dnok) dn = zero4; }
;                         res[bj] = bb[bj] + w0[bj] * up + w1[bj] * cur + w2[bj] * dn; }
;                     if (store_ok) {
;                         float o[4];
; #pragma unroll
;                         for (int j = 0; j < 4; ++j) { const float gg = res[1][j]; o[j] = gg * __builtin_amdgcn_rcpf(1.f + __expf(-gg)) * res[0][j]; }
;                         u32x2 w; w.x = cvt_pk_bf16(o[0], o[1]); w.y = cvt_pk_bf16(o[2], o[3]);
;                         *(u32x2*)(ACT + (size_t)(seqrow + t) * 2816 + ch0 + 4 * n) = w; } } }
	v_pk_fma_f32 v[202:203], v[156:157], v[176:177], v[168:169]
	v_pk_fma_f32 v[44:45], v[44:45], v[160:161], v[202:203]
	v_pk_fma_f32 v[44:45], v[164:165], v[196:197], v[44:45]
	ds_read_b64 v[176:177], v244 offset:768
	v_mad_u32_u24 v251, v39, 16, v201
	ds_read_b64 v[196:197], v251
	v_mul_f32_e32 v208, 0xbfb8aa3b, v66
	v_mul_f32_e32 v209, 0xbfb8aa3b, v67
	v_mul_f32_e32 v210, 0xbfb8aa3b, v68
	v_mul_f32_e32 v211, 0xbfb8aa3b, v69
	v_exp_f32_e32 v208, v208
	v_exp_f32_e32 v209, v209
	v_exp_f32_e32 v210, v210
	v_exp_f32_e32 v211, v211
	v_add_f32_e32 v208, 1.0, v208
	v_add_f32_e32 v209, 1.0, v209
	v_add_f32_e32 v210, 1.0, v210
	v_add_f32_e32 v211, 1.0, v211
	v_rcp_f32_e32 v208, v208
	v_rcp_f32_e32 v209, v209
	v_rcp_f32_e32 v210, v210
	v_rcp_f32_e32 v211, v211
	v_mul_f32_e32 v66, v66, v208
	v_mul_f32_e32 v67, v67, v209
	v_mul_f32_e32 v68, v68, v210
	v_mul_f32_e32 v69, v69, v211
	v_mul_f32_e32 v66, v70, v66
	v_mul_f32_e32 v67, v71, v67
	v_mul_f32_e32 v68, v72, v68
	v_mul_f32_e32 v69, v73, v69
	v_cvt_pk_bf16_f32 v212, v66, v67
	v_cvt_pk_bf16_f32 v213, v68, v69
	v_mad_u32_u24 v221, v227, s29, v247
	s_and_saveexec_b64 s[30:31], s[12:13]
	global_store_dwordx2 v221, v[212:213], s[10:11] offset:8
	s_mov_b64 exec, s[30:31]
	v_mul_f32_e32 v208, 0xbfb8aa3b, v58
	v_mul_f32_e32 v209, 0xbfb8aa3b, v59
	v_mul_f32_e32 v210, 0xbfb8aa3b, v60
	v_mul_f32_e32 v211, 0xbfb8aa3b, v61
	v_exp_f32_e32 v208, v208
	v_exp_f32_e32 v209, v209
	v_exp_f32_e32 v210, v210
	v_exp_f32_e32 v211, v211
	v_add_f32_e32 v208, 1.0, v208
	v_add_f32_e32 v209, 1.0, v209
	v_add_f32_e32 v210, 1.0, v210
	v_add_f32_e32 v211, 1.0, v211
	v_rcp_f32_e32 v208, v208
	v_rcp_f32_e32 v209, v209
	v_rcp_f32_e32 v210, v210
	v_rcp_f32_e32 v211, v211
	v_mul_f32_e32 v58, v58, v208
	v_mul_f32_e32 v59, v59, v209
	v_mul_f32_e32 v60, v60, v210
	v_mul_f32_e32 v61, v61, v211
	v_mul_f32_e32 v58, v62, v58
	v_mul_f32_e32 v59, v63, v59
	v_mul_f32_e32 v60, v64, v60
	v_mul_f32_e32 v61, v65, v61
	v_cvt_pk_bf16_f32 v218, v58, v59
	v_cvt_pk_bf16_f32 v219, v60, v61
	v_mad_u32_u24 v40, v231, s29, v247
	s_and_saveexec_b64 s[30:31], s[14:15]
	global_store_dwordx2 v40, v[218:219], s[10:11] offset:8
	s_mov_b64 exec, s[30:31]
	v_mul_f32_e32 v208, 0xbfb8aa3b, v50
	v_mul_f32_e32 v209, 0xbfb8aa3b, v51
	v_mul_f32_e32 v210, 0xbfb8aa3b, v52
	v_mul_f32_e32 v211, 0xbfb8aa3b, v53
	v_exp_f32_e32 v208, v208
	v_exp_f32_e32 v209, v209
	v_exp_f32_e32 v210, v210
	v_exp_f32_e32 v211, v211
	v_add_f32_e32 v208, 1.0, v208
	v_add_f32_e32 v209, 1.0, v209
	v_add_f32_e32 v210, 1.0, v210
	v_add_f32_e32 v211, 1.0, v211
	v_rcp_f32_e32 v208, v208
	v_rcp_f32_e32 v209, v209
	v_rcp_f32_e32 v210, v210
	v_rcp_f32_e32 v211, v211
	v_mul_f32_e32 v50, v50, v208
	v_mul_f32_e32 v51, v51, v209
	v_mul_f32_e32 v52, v52, v210
	v_mul_f32_e32 v53, v53, v211
	v_mul_f32_e32 v50, v54, v50
	v_mul_f32_e32 v51, v55, v51
	v_mul_f32_e32 v52, v56, v52
	v_mul_f32_e32 v53, v57, v53
	v_cvt_pk_bf16_f32 v212, v50, v51
	v_cvt_pk_bf16_f32 v213, v52, v53
	v_mad_u32_u24 v221, v232, s29, v247
	s_and_saveexec_b64 s[30:31], s[16:17]
	global_store_dwordx2 v221, v[212:213], s[10:11] offset:8
	s_mov_b64 exec, s[30:31]
	v_mul_f32_e32 v208, 0xbfb8aa3b, v42
	v_mul_f32_e32 v209, 0xbfb8aa3b, v43
	v_mul_f32_e32 v210, 0xbfb8aa3b, v44
	v_mul_f32_e32 v211, 0xbfb8aa3b, v45
	v_exp_f32_e32 v208, v208
	v_exp_f32_e32 v209, v209
	v_exp_f32_e32 v210, v210
	v_exp_f32_e32 v211, v211
	v_add_f32_e32 v208, 1.0, v208
	v_add_f32_e32 v209, 1.0, v209
	v_add_f32_e32 v210, 1.0, v210
	v_add_f32_e32 v211, 1.0, v211
	v_rcp_f32_e32 v208, v208
	v_rcp_f32_e32 v209, v209
	v_rcp_f32_e32 v210, v210
	v_rcp_f32_e32 v211, v211
	v_mul_f32_e32 v42, v42, v208
	v_mul_f32_e32 v43, v43, v209
	v_mul_f32_e32 v44, v44, v210
	v_mul_f32_e32 v45, v45, v211
	v_mul_f32_e32 v42, v46, v42
	v_mul_f32_e32 v43, v47, v43
	v_mul_f32_e32 v44, v48, v44
	v_mul_f32_e32 v45, v49, v45
	v_cvt_pk_bf16_f32 v218, v42, v43
	v_cvt_pk_bf16_f32 v219, v44, v45
	v_mad_u32_u24 v40, v233, s29, v247
	s_and_saveexec_b64 s[30:31], s[18:19]
	global_store_dwordx2 v40, v[218:219], s[10:11] offset:8
	s_mov_b64 exec, s[30:31]
	ds_write_b64 v243, v[32:33]
	ds_write_b64 v243, v[24:25] offset:256
	ds_write_b64 v243, v[16:17] offset:512
	ds_write_b64 v243, v[8:9] offset:768
	s_waitcnt lgkmcnt(10)
	v_pk_fma_f32 v[202:203], v[138:139], v[170:171], v[150:151]
	v_pk_fma_f32 v[30:31], v[30:31], v[142:143], v[202:203]
	v_pk_fma_f32 v[30:31], v[146:147], v[178:179], v[30:31]
	v_mad_u32_u24 v250, v38, 24, v199
	ds_read_b64 v[170:171], v250
	ds_read_b64 v[178:179], v243 offset:16
	s_waitcnt lgkmcnt(10)
	v_pk_fma_f32 v[202:203], v[138:139], v[172:173], v[150:151]
	v_pk_fma_f32 v[22:23], v[22:23], v[142:143], v[202:203]
	v_pk_fma_f32 v[22:23], v[146:147], v[180:181], v[22:23]
	ds_read_b64 v[172:173], v244 offset:256
	ds_read_b64 v[180:181], v243 offset:272
	s_waitcnt lgkmcnt(10)
	v_pk_fma_f32 v[202:203], v[138:139], v[174:175], v[150:151]
	v_pk_fma_f32 v[14:15], v[14:15], v[142:143], v[202:203]
	v_pk_fma_f32 v[14:15], v[146:147], v[194:195], v[14:15]
	ds_read_b64 v[174:175], v244 offset:512
	ds_read_b64 v[194:195], v243 offset:528
	s_waitcnt lgkmcnt(10)
	v_pk_fma_f32 v[202:203], v[138:139], v[176:177], v[150:151]
	v_pk_fma_f32 v[6:7], v[6:7], v[142:143], v[202:203]
	v_pk_fma_f32 v[6:7], v[146:147], v[196:197], v[6:7]
	ds_read_b64 v[176:177], v244 offset:768
	v_mad_u32_u24 v251, v39, 24, v201
	ds_read_b64 v[196:197], v251
	ds_write_b64 v243, v[26:27]
	ds_write_b64 v243, v[18:19] offset:256
	ds_write_b64 v243, v[10:11] offset:512
	ds_write_b64 v243, v[2:3] offset:768
	s_waitcnt lgkmcnt(10)
; #define PG8_LAS __attribute__((address_space(3)))
; __device__ __forceinline__ unsigned cvt_pk_bf16(float lo, float hi) { unsigned r; asm volatile("v_cvt_pk_bf16_f32 %0, %1, %2" : "=v"(r) : "v"(lo), "v"(hi)); return r; }
;     __device__ __forceinline__ void operator()(const f32x4 (&acc)[2][2][4][2], const Unit& u, int wr, int wc, int fr, int fq) const {
;     ...
;                 for (int m = 0; m < 4; ++m) { const int r = 128 * ai + 64 * wr + 16 * m + fr, t = tstart + r;
;                     const bool upok = t >= 1, dnok = (t + 1) < T, store_ok = (r >= vlo) && (r < vhi) && (t < T);
;                     f32x4 res[2];
; #pragma unroll
;                     for (int bj = 0; bj < 2; ++bj) { const f32x4 cur = acc[ai][bj][m][n];
;                         f32x4 su = cur, sd = cur;
;                         if (m > 0) { if (fr == 15) su = acc[ai][bj][m > 0 ? m - 1 : 0][n]; }
;                         if (m < 3) { if (fr == 0) sd = acc[ai][bj][m < 3 ? m + 1 : 3][n]; }
;                         f32x4 up, dn;
;                         up[0] = dpp_ror1(su[0]); up[1] = dpp_ror1(su[1]); up[2] = dpp_ror1(su[2]); up[3] = dpp_ror1(su[3]);
;                         dn[0] = dpp_ror15(sd[0]); dn[1] = dpp_ror15(sd[1]); dn[2] = dpp_ror15(sd[2]); dn[3] = dpp_ror15(sd[3]);
;                         if (m == 0) { f32x4 halo = zero4; if (blk > 0) halo = *(const PG8_LAS f32x4*)(xb + (((((blk - 1) * 2 + 1) * 4 + wc) * 4 + fq) * 16 + (bj * 2 + n) * 4)); if (fr == 0) up = halo; }
;                         if (m == 3) { f32x4 halo = zero4; if (blk < 3) halo = *(const PG8_LAS f32x4*)(xb + (((((blk + 1) * 2 + 0) * 4 + wc) * 4 + fq) * 16 + (bj * 2 + n) * 4)); if (fr == 15) dn = halo; }
;                         if (edge) { if (!upok) up = zero4; if (!dnok) dn = zero4; }
;                         res[bj] = bb[bj] + w0[bj] * up + w1[bj] * cur + w2[bj] * dn; }
;                     if (store_ok) {
;                         float o[4];
; #pragma unroll
;                         for (int j = 0; j < 4; ++j) { const float gg = res[1][j]; o[j] = gg * __builtin_amdgcn_rcpf(1.f + __expf(-gg)) * res[0][j]; }
;                         u32x2 w; w.x = cvt_pk_bf16(o[0], o[1]); w.y = cvt_pk_bf16(o[2], o[3]);
;                         *(u32x2*)(ACT + (size_t)(seqrow + t) * 2816 + ch0 + 4 * n) = w; } } }
	v_pk_fma_f32 v[202:203], v[140:141], v[170:171], v[152:153]
	v_pk_fma_f32 v[32:33], v[32:33], v[144:145], v[202:203]
	v_pk_fma_f32 v[32:33], v[148:149], v[178:179], v[32:33]
	v_mad_u32_u24 v250, v38, 48, v199
	ds_read_b64 v[170:171], v250
	ds_read_b64 v[178:179], v243 offset:16
	s_waitcnt lgkmcnt(10)
	v_pk_fma_f32 v[202:203], v[140:141], v[172:173], v[152:153]
	v_pk_fma_f32 v[24:25], v[24:25], v[144:145], v[202:203]
	v_pk_fma_f32 v[24:25], v[148:149], v[180:181], v[24:25]
	ds_read_b64 v[172:173], v244 offset:256
	ds_read_b64 v[180:181], v243 offset:272
	s_waitcnt lgkmcnt(10)
	v_pk_fma_f32 v[202:203], v[140:141], v[174:175], v[152:153]
	v_pk_fma_f32 v[16:17], v[16:17], v[144:145], v[202:203]
	v_pk_fma_f32 v[16:17], v[148:149], v[194:195], v[16:17]
	ds_read_b64 v[174:175], v244 offset:512
	ds_read_b64 v[194:195], v243 offset:528
	s_waitcnt lgkmcnt(10)
	v_pk_fma_f32 v[202:203], v[140:141], v[176:177], v[152:153]
	v_pk_fma_f32 v[8:9], v[8:9], v[144:145], v[202:203]
	v_pk_fma_f32 v[8:9], v[148:149], v[196:197], v[8:9]
	ds_read_b64 v[176:177], v244 offset:768
	v_mad_u32_u24 v251, v39, 48, v201
	ds_read_b64 v[196:197], v251
	ds_write_b64 v243, v[28:29]
	ds_write_b64 v243, v[20:21] offset:256
	ds_write_b64 v243, v[12:13] offset:512
	ds_write_b64 v243, v[4:5] offset:768
	s_waitcnt lgkmcnt(10)
	v_pk_fma_f32 v[202:203], v[154:155], v[170:171], v[166:167]
	v_pk_fma_f32 v[26:27], v[26:27], v[158:159], v[202:203]
	v_pk_fma_f32 v[26:27], v[162:163], v[178:179], v[26:27]
	v_mad_u32_u24 v250, v38, 56, v199
	ds_read_b64 v[170:171], v250
	ds_read_b64 v[178:179], v243 offset:16
	s_waitcnt lgkmcnt(10)
	v_pk_fma_f32 v[202:203], v[154:155], v[172:173], v[166:167]
	v_pk_fma_f32 v[18:19], v[18:19], v[158:159], v[202:203]
	v_pk_fma_f32 v[18:19], v[162:163], v[180:181], v[18:19]
	ds_read_b64 v[172:173], v244 offset:256
	ds_read_b64 v[180:181], v243 offset:272
	s_waitcnt lgkmcnt(10)
	v_pk_fma_f32 v[202:203], v[154:155], v[174:175], v[166:167]
	v_pk_fma_f32 v[10:11], v[10:11], v[158:159], v[202:203]
	v_pk_fma_f32 v[10:11], v[162:163], v[194:195], v[10:11]
	ds_read_b64 v[174:175], v244 offset:512
	ds_read_b64 v[194:195], v243 offset:528
	s_waitcnt lgkmcnt(10)
	v_pk_fma_f32 v[202:203], v[154:155], v[176:177], v[166:167]
	v_pk_fma_f32 v[2:3], v[2:3], v[158:159], v[202:203]
	v_pk_fma_f32 v[2:3], v[162:163], v[196:197], v[2:3]
	ds_read_b64 v[176:177], v244 offset:768
	v_mad_u32_u24 v251, v39, 56, v201
	ds_read_b64 v[196:197], v251
	s_waitcnt lgkmcnt(6)
	v_pk_fma_f32 v[202:203], v[156:157], v[170:171], v[168:169]
	v_pk_fma_f32 v[28:29], v[28:29], v[160:161], v[202:203]
	v_pk_fma_f32 v[28:29], v[164:165], v[178:179], v[28:29]
	s_waitcnt lgkmcnt(4)
	v_pk_fma_f32 v[202:203], v[156:157], v[172:173], v[168:169]
	v_pk_fma_f32 v[20:21], v[20:21], v[160:161], v[202:203]
	v_pk_fma_f32 v[20:21], v[164:165], v[180:181], v[20:21]
	s_waitcnt lgkmcnt(2)
	v_pk_fma_f32 v[202:203], v[156:157], v[174:175], v[168:169]
	v_pk_fma_f32 v[12:13], v[12:13], v[160:161], v[202:203]
	v_pk_fma_f32 v[12:13], v[164:165], v[194:195], v[12:13]
	s_waitcnt lgkmcnt(0)
	v_pk_fma_f32 v[202:203], v[156:157], v[176:177], v[168:169]
	v_pk_fma_f32 v[4:5], v[4:5], v[160:161], v[202:203]
	v_pk_fma_f32 v[4:5], v[164:165], v[196:197], v[4:5]
	v_mul_f32_e32 v208, 0xbfb8aa3b, v26
	v_mul_f32_e32 v209, 0xbfb8aa3b, v27
	v_mul_f32_e32 v210, 0xbfb8aa3b, v28
	v_mul_f32_e32 v211, 0xbfb8aa3b, v29
	v_exp_f32_e32 v208, v208
	v_exp_f32_e32 v209, v209
	v_exp_f32_e32 v210, v210
	v_exp_f32_e32 v211, v211
	v_add_f32_e32 v208, 1.0, v208
	v_add_f32_e32 v209, 1.0, v209
	v_add_f32_e32 v210, 1.0, v210
	v_add_f32_e32 v211, 1.0, v211
	v_rcp_f32_e32 v208, v208
	v_rcp_f32_e32 v209, v209
	v_rcp_f32_e32 v210, v210
	v_rcp_f32_e32 v211, v211
	v_mul_f32_e32 v26, v26, v208
	v_mul_f32_e32 v27, v27, v209
	v_mul_f32_e32 v28, v28, v210
	v_mul_f32_e32 v29, v29, v211
	v_mul_f32_e32 v26, v30, v26
	v_mul_f32_e32 v27, v31, v27
	v_mul_f32_e32 v28, v32, v28
	v_mul_f32_e32 v29, v33, v29
	v_cvt_pk_bf16_f32 v212, v26, v27
	v_cvt_pk_bf16_f32 v213, v28, v29
	v_mad_u32_u24 v221, v234, s29, v247
	s_and_saveexec_b64 s[30:31], s[20:21]
	global_store_dwordx2 v221, v[212:213], s[10:11] offset:8
	s_mov_b64 exec, s[30:31]
	v_mul_f32_e32 v208, 0xbfb8aa3b, v18
	v_mul_f32_e32 v209, 0xbfb8aa3b, v19
	v_mul_f32_e32 v210, 0xbfb8aa3b, v20
	v_mul_f32_e32 v211, 0xbfb8aa3b, v21
	v_exp_f32_e32 v208, v208
	v_exp_f32_e32 v209, v209
	v_exp_f32_e32 v210, v210
	v_exp_f32_e32 v211, v211
	v_add_f32_e32 v208, 1.0, v208
	v_add_f32_e32 v209, 1.0, v209
	v_add_f32_e32 v210, 1.0, v210
	v_add_f32_e32 v211, 1.0, v211
	v_rcp_f32_e32 v208, v208
	v_rcp_f32_e32 v209, v209
	v_rcp_f32_e32 v210, v210
	v_rcp_f32_e32 v211, v211
	v_mul_f32_e32 v18, v18, v208
	v_mul_f32_e32 v19, v19, v209
	v_mul_f32_e32 v20, v20, v210
	v_mul_f32_e32 v21, v21, v211
	v_mul_f32_e32 v18, v22, v18
	v_mul_f32_e32 v19, v23, v19
	v_mul_f32_e32 v20, v24, v20
	v_mul_f32_e32 v21, v25, v21
	v_cvt_pk_bf16_f32 v218, v18, v19
	v_cvt_pk_bf16_f32 v219, v20, v21
	v_mad_u32_u24 v40, v235, s29, v247
	s_and_saveexec_b64 s[30:31], s[22:23]
	global_store_dwordx2 v40, v[218:219], s[10:11] offset:8
	s_mov_b64 exec, s[30:31]
	v_mul_f32_e32 v208, 0xbfb8aa3b, v10
	v_mul_f32_e32 v209, 0xbfb8aa3b, v11
	v_mul_f32_e32 v210, 0xbfb8aa3b, v12
	v_mul_f32_e32 v211, 0xbfb8aa3b, v13
	v_exp_f32_e32 v208, v208
	v_exp_f32_e32 v209, v209
	v_exp_f32_e32 v210, v210
	v_exp_f32_e32 v211, v211
	v_add_f32_e32 v208, 1.0, v208
	v_add_f32_e32 v209, 1.0, v209
	v_add_f32_e32 v210, 1.0, v210
	v_add_f32_e32 v211, 1.0, v211
	v_rcp_f32_e32 v208, v208
	v_rcp_f32_e32 v209, v209
	v_rcp_f32_e32 v210, v210
	v_rcp_f32_e32 v211, v211
	v_mul_f32_e32 v10, v10, v208
	v_mul_f32_e32 v11, v11, v209
	v_mul_f32_e32 v12, v12, v210
	v_mul_f32_e32 v13, v13, v211
	v_mul_f32_e32 v10, v14, v10
	v_mul_f32_e32 v11, v15, v11
	v_mul_f32_e32 v12, v16, v12
	v_mul_f32_e32 v13, v17, v13
	v_cvt_pk_bf16_f32 v212, v10, v11
	v_cvt_pk_bf16_f32 v213, v12, v13
	v_mad_u32_u24 v221, v236, s29, v247
	s_and_saveexec_b64 s[30:31], s[24:25]
	global_store_dwordx2 v221, v[212:213], s[10:11] offset:8
	s_mov_b64 exec, s[30:31]
	v_mul_f32_e32 v208, 0xbfb8aa3b, v2
	v_mul_f32_e32 v209, 0xbfb8aa3b, v3
	v_mul_f32_e32 v210, 0xbfb8aa3b, v4
	v_mul_f32_e32 v211, 0xbfb8aa3b, v5
	v_exp_f32_e32 v208, v208
	v_exp_f32_e32 v209, v209
	v_exp_f32_e32 v210, v210
	v_exp_f32_e32 v211, v211
	v_add_f32_e32 v208, 1.0, v208
	v_add_f32_e32 v209, 1.0, v209
	v_add_f32_e32 v210, 1.0, v210
	v_add_f32_e32 v211, 1.0, v211
	v_rcp_f32_e32 v208, v208
	v_rcp_f32_e32 v209, v209
	v_rcp_f32_e32 v210, v210
	v_rcp_f32_e32 v211, v211
	v_mul_f32_e32 v2, v2, v208
	v_mul_f32_e32 v3, v3, v209
	v_mul_f32_e32 v4, v4, v210
	v_mul_f32_e32 v5, v5, v211
	v_mul_f32_e32 v2, v6, v2
	v_mul_f32_e32 v3, v7, v3
	v_mul_f32_e32 v4, v8, v4
	v_mul_f32_e32 v5, v9, v5
	v_cvt_pk_bf16_f32 v218, v2, v3
	v_cvt_pk_bf16_f32 v219, v4, v5
	v_mad_u32_u24 v40, v237, s29, v247
	s_and_saveexec_b64 s[30:31], s[26:27]
	global_store_dwordx2 v40, v[218:219], s[10:11] offset:8
	s_mov_b64 exec, s[30:31]
	s_branch .Lec_done

; template <class Epi, class Sched, bool ALIGN_EPI = false, bool SP2 = false>
; __device__ __forceinline__ void gemm_phase(PG8_LAS unsigned char* lds, const Gemm g, const Sched& S, const Epi& E) {
;     ...
;         if constexpr (!Epi::AFTER_DRAIN) { E(acc, cur, wr, wc, fr, fq); S.done(cur); }
;         if (!has_next) break;
.Lec_done:
	s_nop 0
	s_mov_b64 s[2:3], exec
